# WIN: row statistics prefetched in the last K iteration as well (one partial per lane + permlane reduction)
# baseline (speedup 1.0000x reference)
.Lwinskip_5:
	s_setprio 0
	s_barrier
	s_add_i32 s79, s75, s8
	s_add_i32 m0, s79, 0xffffff80
	ds_read_b128 v[182:185], v171 offset:49152
	ds_read_b128 v[186:189], v171 offset:50176
	ds_read_b128 v[190:193], v171 offset:51200
	ds_read_b128 v[194:197], v171 offset:52224
	ds_read_b128 v[208:211], v171 offset:53248
	ds_read_b128 v[212:215], v171 offset:54272
	ds_read_b128 v[216:219], v171 offset:55296
	ds_read_b128 v[232:235], v171 offset:56320
	global_load_lds_dwordx4 v166, s[66:67] offset:128
	s_add_i32 m0, s79, 0x1f80
	s_nop 0
	global_load_lds_dwordx4 v94, s[66:67] offset:128
	s_add_i32 s79, s76, s8
	s_add_u32 s66, s66, 0x40080
	s_addc_u32 s67, s67, 0
	s_mov_b32 m0, s79
	s_nop 0
	global_load_lds_dwordx4 v166, s[66:67]
	s_add_i32 m0, s79, 0x2000
	s_nop 0
	global_load_lds_dwordx4 v94, s[66:67]
	s_add_u32 s68, s68, 0xfffc0080
	s_addc_u32 s69, s69, -1
	s_mov_b32 m0, s33
	s_nop 0
	global_load_lds_dwordx4 v166, s[68:69]
	s_mov_b32 m0, s80
	s_nop 0
	global_load_lds_dwordx4 v94, s[68:69]
	s_waitcnt vmcnt(8)
	s_waitcnt lgkmcnt(0)
	s_cmp_lg_u32 s74, 12
	s_cbranch_scc1 .Lwin_nopf
	s_lshl_b32 s79, s6, 8
	s_add_i32 s79, s79, s28
	v_mbcnt_lo_u32_b32 v203, -1, 0
	v_mbcnt_hi_u32_b32 v203, -1, v203
	v_or_b32_e32 v202, s79, v97
	v_lshrrev_b32_e32 v203, 2, v203
	v_and_b32_e32 v203, 12, v203
	v_lshl_add_u32 v202, v202, 4, v203
	global_load_dword v236, v202, s[16:17]
	global_load_dword v237, v202, s[16:17] offset:256
	global_load_dword v238, v202, s[16:17] offset:512
	global_load_dword v239, v202, s[16:17] offset:768
	global_load_dword v240, v202, s[16:17] offset:2048
	global_load_dword v241, v202, s[16:17] offset:2304
	global_load_dword v220, v202, s[16:17] offset:2560
	global_load_dword v221, v202, s[16:17] offset:2816
.Lwin_nopf:
	s_barrier
	s_setprio 1
	s_waitcnt lgkmcnt(0)
	s_cmp_lg_u32 vcc_lo, 0
	s_cbranch_scc1 .Lwinskip_6
	v_mfma_f32_16x16x32_bf16 v[98:101], v[134:137], v[182:185], v[98:101]
	v_mfma_f32_16x16x32_bf16 v[90:93], v[142:145], v[182:185], v[90:93]
	v_mfma_f32_16x16x32_bf16 v[86:89], v[134:137], v[190:193], v[86:89]
	v_mfma_f32_16x16x32_bf16 v[82:85], v[142:145], v[190:193], v[82:85]
	v_mfma_f32_16x16x32_bf16 v[78:81], v[134:137], v[208:211], v[78:81]
	v_mfma_f32_16x16x32_bf16 v[74:77], v[142:145], v[208:211], v[74:77]
	v_mfma_f32_16x16x32_bf16 v[70:73], v[134:137], v[216:219], v[70:73]
	v_mfma_f32_16x16x32_bf16 v[66:69], v[142:145], v[216:219], v[66:69]
	v_mfma_f32_16x16x32_bf16 v[98:101], v[138:141], v[186:189], v[98:101]
	v_mfma_f32_16x16x32_bf16 v[90:93], v[146:149], v[186:189], v[90:93]
	v_mfma_f32_16x16x32_bf16 v[86:89], v[138:141], v[194:197], v[86:89]
	v_mfma_f32_16x16x32_bf16 v[82:85], v[146:149], v[194:197], v[82:85]
	v_mfma_f32_16x16x32_bf16 v[78:81], v[138:141], v[212:215], v[78:81]
	v_mfma_f32_16x16x32_bf16 v[74:77], v[146:149], v[212:215], v[74:77]
	v_mfma_f32_16x16x32_bf16 v[70:73], v[138:141], v[232:235], v[70:73]
	v_mfma_f32_16x16x32_bf16 v[66:69], v[146:149], v[232:235], v[66:69]

.Lwinskip_7:
	s_setprio 0
	s_barrier
	s_add_i32 s74, s74, 2
	s_add_u32 s72, s72, 0x100
	s_addc_u32 s73, s73, 0
	s_add_u32 s64, s64, 0x100
	s_addc_u32 s65, s65, 0
	s_cmp_gt_u32 s74, 13
	s_cbranch_scc0 .LBB0_403
	s_lshl_b32 s57, s6, 8
	s_add_i32 s57, s57, s28
	v_or_b32_e32 v184, s57, v97
	v_add_u32_e32 v182, 0x80, v184
	v_ashrrev_i32_e32 v185, 31, v184
	v_ashrrev_i32_e32 v183, 31, v182
	s_and_b64 vcc, exec, s[30:31]
	s_cbranch_vccz .LBB0_406
	s_barrier

.LBB0_421:
	s_waitcnt vmcnt(0)
	v_mov_b32_e32 v146, v236
	v_mov_b32_e32 v147, v237
	v_mov_b32_e32 v148, v238
	v_mov_b32_e32 v149, v239
	v_mov_b32_e32 v150, v240
	v_mov_b32_e32 v151, v241
	v_mov_b32_e32 v152, v220
	v_mov_b32_e32 v153, v221
	v_permlane16_swap_b32_e32 v236, v146
	v_permlane16_swap_b32_e32 v237, v147
	v_permlane16_swap_b32_e32 v238, v148
	v_permlane16_swap_b32_e32 v239, v149
	v_permlane16_swap_b32_e32 v240, v150
	v_permlane16_swap_b32_e32 v241, v151
	v_permlane16_swap_b32_e32 v220, v152
	v_permlane16_swap_b32_e32 v221, v153
	v_add_f32_e32 v236, v236, v146
	v_add_f32_e32 v237, v237, v147
	v_add_f32_e32 v238, v238, v148
	v_add_f32_e32 v239, v239, v149
	v_add_f32_e32 v240, v240, v150
	v_add_f32_e32 v241, v241, v151
	v_add_f32_e32 v220, v220, v152
	v_add_f32_e32 v221, v221, v153
	v_mov_b32_e32 v146, v236
	v_mov_b32_e32 v147, v237
	v_mov_b32_e32 v148, v238
	v_mov_b32_e32 v149, v239
	v_mov_b32_e32 v150, v240
	v_mov_b32_e32 v151, v241
	v_mov_b32_e32 v152, v220
	v_mov_b32_e32 v153, v221
	v_permlane32_swap_b32_e32 v236, v146
	v_permlane32_swap_b32_e32 v237, v147
	v_permlane32_swap_b32_e32 v238, v148
	v_permlane32_swap_b32_e32 v239, v149
	v_permlane32_swap_b32_e32 v240, v150
	v_permlane32_swap_b32_e32 v241, v151
	v_permlane32_swap_b32_e32 v220, v152
	v_permlane32_swap_b32_e32 v221, v153
	v_add_f32_e32 v236, v236, v146
	v_add_f32_e32 v237, v237, v147
	v_add_f32_e32 v238, v238, v148
	v_add_f32_e32 v239, v239, v149
	v_add_f32_e32 v240, v240, v150
	v_add_f32_e32 v241, v241, v151
	v_add_f32_e32 v220, v220, v152
	v_add_f32_e32 v221, v221, v153
	v_fmamk_f32 v236, v236, 0x3a800000, v222
	v_fmamk_f32 v237, v237, 0x3a800000, v222
	v_fmamk_f32 v238, v238, 0x3a800000, v222
	v_fmamk_f32 v239, v239, 0x3a800000, v222
	v_fmamk_f32 v240, v240, 0x3a800000, v222
	v_fmamk_f32 v241, v241, 0x3a800000, v222
	v_fmamk_f32 v220, v220, 0x3a800000, v222
	v_fmamk_f32 v221, v221, 0x3a800000, v222
	v_rsq_f32_e32 v164, v236
	v_rsq_f32_e32 v162, v237
	v_rsq_f32_e32 v156, v238
	v_rsq_f32_e32 v154, v239
	v_rsq_f32_e32 v144, v240
	v_rsq_f32_e32 v142, v241
	v_rsq_f32_e32 v138, v220
	v_rsq_f32_e32 v134, v221
	s_mov_b64 s[78:79], -1
	s_add_i32 s66, s87, s81
	v_lshlrev_b32_e32 v135, 5, v184
	s_andn2_b64 vcc, exec, s[74:75]
	s_cbranch_vccz .LBB0_437
	s_xor_b64 s[76:77], s[76:77], -1
	s_mov_b64 s[74:75], -1
	s_and_b64 vcc, exec, s[76:77]
	s_cbranch_vccz .LBB0_434
	s_xor_b64 s[74:75], s[72:73], -1
	s_mov_b64 s[72:73], -1
	s_and_b64 vcc, exec, s[74:75]
	s_cbranch_vccz .LBB0_431
	s_xor_b64 s[72:73], s[70:71], -1
	s_mov_b64 s[70:71], -1
	s_and_b64 vcc, exec, s[72:73]
	s_cbranch_vccz .LBB0_428
	s_and_b64 s[68:69], s[54:55], s[68:69]
	s_andn2_b64 vcc, exec, s[68:69]
	s_cbranch_vccnz .LBB0_427
	v_pk_mul_f32 v[136:137], v[132:133], v[164:165] op_sel_hi:[1,0]
	v_pk_mul_f32 v[140:141], v[130:131], v[164:165] op_sel_hi:[1,0]
	v_mul_f32_e32 v136, 0xbfb8aa3b, v136
	v_mul_f32_e32 v139, 0xbfb8aa3b, v140
	v_exp_f32_e32 v139, v139
	v_exp_f32_e32 v136, v136
	s_ashr_i32 s67, s57, 11
	s_mul_hi_i32 s69, s67, 0x1414000
	v_add_f32_e32 v139, 1.0, v139
	v_add_f32_e32 v136, 1.0, v136
	v_rcp_f32_e32 v146, v139
	v_mul_f32_e32 v139, 0xbfb8aa3b, v141
	v_rcp_f32_e32 v148, v136
	v_mul_f32_e32 v136, 0xbfb8aa3b, v137
	v_exp_f32_e32 v139, v139
	v_exp_f32_e32 v136, v136
	s_mul_i32 s67, s67, 0x1414000
	v_and_b32_e32 v0, 0xf9e0, v135
	v_add_f32_e32 v139, 1.0, v139
	v_add_f32_e32 v136, 1.0, v136
	v_rcp_f32_e32 v147, v139
	v_rcp_f32_e32 v149, v136
	s_add_u32 s68, s52, s67
	s_addc_u32 s69, s53, s69
	v_lshlrev_b32_e32 v0, 2, v0
	v_lshl_add_u64 v[136:137], s[68:69], 0, v[0:1]
	v_lshlrev_b32_e32 v0, 2, v170
	v_lshl_add_u64 v[136:137], v[136:137], 0, v[0:1]
	flat_store_dwordx4 v[136:137], v[146:149]
	v_pk_mul_f32 v[140:141], v[128:129], v[164:165] op_sel_hi:[1,0]
	s_movk_i32 s70, 0x1000
	v_pk_mul_f32 v[146:147], v[126:127], v[164:165] op_sel_hi:[1,0]
	s_mov_b32 s67, 0x1414000
	v_mul_f32_e32 v139, 0xbfb8aa3b, v146
	v_exp_f32_e32 v139, v139
	s_nop 0
	v_add_f32_e32 v139, 1.0, v139
	v_rcp_f32_e32 v146, v139
	v_mul_f32_e32 v139, 0xbfb8aa3b, v147
	v_exp_f32_e32 v139, v139
	s_nop 0
	v_add_f32_e32 v139, 1.0, v139
	v_rcp_f32_e32 v147, v139
	v_mul_f32_e32 v139, 0xbfb8aa3b, v140
	v_exp_f32_e32 v139, v139
	s_nop 0
	v_add_f32_e32 v139, 1.0, v139
	v_rcp_f32_e32 v148, v139
	v_mul_f32_e32 v139, 0xbfb8aa3b, v141
	v_exp_f32_e32 v139, v139
	v_pk_mul_f32 v[140:141], v[124:125], v[162:163] op_sel_hi:[1,0]
	v_add_f32_e32 v139, 1.0, v139
	v_rcp_f32_e32 v149, v139
	flat_store_dwordx4 v[136:137], v[146:149] offset:64
	s_nop 1
	v_pk_mul_f32 v[146:147], v[122:123], v[162:163] op_sel_hi:[1,0]
	s_nop 0
	v_mul_f32_e32 v139, 0xbfb8aa3b, v146
	v_exp_f32_e32 v139, v139
	s_nop 0
	v_add_f32_e32 v139, 1.0, v139
	v_rcp_f32_e32 v146, v139
	v_mul_f32_e32 v139, 0xbfb8aa3b, v147
	v_exp_f32_e32 v139, v139
	s_nop 0
	v_add_f32_e32 v139, 1.0, v139
	v_rcp_f32_e32 v147, v139
	v_mul_f32_e32 v139, 0xbfb8aa3b, v140
	v_exp_f32_e32 v139, v139
	s_nop 0
	v_add_f32_e32 v139, 1.0, v139
	v_rcp_f32_e32 v148, v139
	v_mul_f32_e32 v139, 0xbfb8aa3b, v141
	v_exp_f32_e32 v139, v139
	v_pk_mul_f32 v[140:141], v[120:121], v[162:163] op_sel_hi:[1,0]
	v_add_f32_e32 v139, 1.0, v139
	v_rcp_f32_e32 v149, v139
	flat_store_dwordx4 v[136:137], v[146:149] offset:2048
	s_nop 1
	v_pk_mul_f32 v[146:147], v[118:119], v[162:163] op_sel_hi:[1,0]
	s_nop 0
	v_mul_f32_e32 v139, 0xbfb8aa3b, v146
	v_exp_f32_e32 v139, v139
	s_nop 0
	v_add_f32_e32 v139, 1.0, v139
	v_rcp_f32_e32 v146, v139
	v_mul_f32_e32 v139, 0xbfb8aa3b, v147
	v_exp_f32_e32 v139, v139
	s_nop 0
	v_add_f32_e32 v139, 1.0, v139
	v_rcp_f32_e32 v147, v139
	v_mul_f32_e32 v139, 0xbfb8aa3b, v140
	v_exp_f32_e32 v139, v139
	s_nop 0
	v_add_f32_e32 v139, 1.0, v139
	v_rcp_f32_e32 v148, v139
	v_mul_f32_e32 v139, 0xbfb8aa3b, v141
	v_exp_f32_e32 v139, v139
	v_pk_mul_f32 v[140:141], v[116:117], v[156:157] op_sel_hi:[1,0]
	v_add_f32_e32 v139, 1.0, v139
	v_rcp_f32_e32 v149, v139
	flat_store_dwordx4 v[136:137], v[146:149] offset:2112
	s_nop 1
	v_pk_mul_f32 v[146:147], v[114:115], v[156:157] op_sel_hi:[1,0]
	v_add_co_u32_e32 v136, vcc, s70, v136
	v_mul_f32_e32 v139, 0xbfb8aa3b, v146
	v_exp_f32_e32 v139, v139
	v_addc_co_u32_e32 v137, vcc, 0, v137, vcc
	v_add_f32_e32 v139, 1.0, v139
	v_rcp_f32_e32 v146, v139
	v_mul_f32_e32 v139, 0xbfb8aa3b, v147
	v_exp_f32_e32 v139, v139
	s_nop 0
	v_add_f32_e32 v139, 1.0, v139
	v_rcp_f32_e32 v147, v139
	v_mul_f32_e32 v139, 0xbfb8aa3b, v140
	v_exp_f32_e32 v139, v139
	s_nop 0
	v_add_f32_e32 v139, 1.0, v139
	v_rcp_f32_e32 v148, v139
	v_mul_f32_e32 v139, 0xbfb8aa3b, v141
	v_exp_f32_e32 v139, v139
	v_pk_mul_f32 v[140:141], v[112:113], v[156:157] op_sel_hi:[1,0]
	v_add_f32_e32 v139, 1.0, v139
	v_rcp_f32_e32 v149, v139
	flat_store_dwordx4 v[136:137], v[146:149]
	s_nop 1
	v_pk_mul_f32 v[146:147], v[110:111], v[156:157] op_sel_hi:[1,0]
	s_nop 0
	v_mul_f32_e32 v139, 0xbfb8aa3b, v146
	v_exp_f32_e32 v139, v139
	s_nop 0
	v_add_f32_e32 v139, 1.0, v139
	v_rcp_f32_e32 v146, v139
	v_mul_f32_e32 v139, 0xbfb8aa3b, v147
	v_exp_f32_e32 v139, v139
	s_nop 0
	v_add_f32_e32 v139, 1.0, v139
	v_rcp_f32_e32 v147, v139
	v_mul_f32_e32 v139, 0xbfb8aa3b, v140
	v_exp_f32_e32 v139, v139
	s_nop 0
	v_add_f32_e32 v139, 1.0, v139
	v_rcp_f32_e32 v148, v139
	v_mul_f32_e32 v139, 0xbfb8aa3b, v141
	v_exp_f32_e32 v139, v139
	v_pk_mul_f32 v[140:141], v[108:109], v[154:155] op_sel_hi:[1,0]
	v_add_f32_e32 v139, 1.0, v139
	v_rcp_f32_e32 v149, v139
	flat_store_dwordx4 v[136:137], v[146:149] offset:64
	s_nop 1
	v_pk_mul_f32 v[146:147], v[106:107], v[154:155] op_sel_hi:[1,0]
	s_nop 0
	v_mul_f32_e32 v139, 0xbfb8aa3b, v146
	v_exp_f32_e32 v139, v139
	s_nop 0
	v_add_f32_e32 v139, 1.0, v139
	v_rcp_f32_e32 v146, v139
	v_mul_f32_e32 v139, 0xbfb8aa3b, v147
	v_exp_f32_e32 v139, v139
	s_nop 0
	v_add_f32_e32 v139, 1.0, v139
	v_rcp_f32_e32 v147, v139
	v_mul_f32_e32 v139, 0xbfb8aa3b, v140
	v_exp_f32_e32 v139, v139
	s_nop 0
	v_add_f32_e32 v139, 1.0, v139
	v_rcp_f32_e32 v148, v139
	v_mul_f32_e32 v139, 0xbfb8aa3b, v141
	v_exp_f32_e32 v139, v139
	v_pk_mul_f32 v[140:141], v[104:105], v[154:155] op_sel_hi:[1,0]
	v_add_f32_e32 v139, 1.0, v139
	v_rcp_f32_e32 v149, v139
	flat_store_dwordx4 v[136:137], v[146:149] offset:2048
	s_nop 1
	v_pk_mul_f32 v[146:147], v[102:103], v[154:155] op_sel_hi:[1,0]
	s_nop 0
	v_mul_f32_e32 v139, 0xbfb8aa3b, v146
	v_exp_f32_e32 v139, v139
	s_nop 0
	v_add_f32_e32 v139, 1.0, v139
	v_rcp_f32_e32 v146, v139
	v_mul_f32_e32 v139, 0xbfb8aa3b, v147
	v_exp_f32_e32 v139, v139
	s_nop 0
	v_add_f32_e32 v139, 1.0, v139
	v_rcp_f32_e32 v147, v139
	v_mul_f32_e32 v139, 0xbfb8aa3b, v140
	v_exp_f32_e32 v139, v139
	s_nop 0
	v_add_f32_e32 v139, 1.0, v139
	v_rcp_f32_e32 v148, v139
	v_mul_f32_e32 v139, 0xbfb8aa3b, v141
	v_exp_f32_e32 v139, v139
	v_pk_mul_f32 v[140:141], v[98:99], v[144:145] op_sel_hi:[1,0]
	v_add_f32_e32 v139, 1.0, v139
	v_rcp_f32_e32 v149, v139
	v_mul_f32_e32 v140, 0xbfb8aa3b, v140
	v_exp_f32_e32 v140, v140
	v_ashrrev_i32_e32 v139, 11, v182
	flat_store_dwordx4 v[136:137], v[146:149] offset:2112
	v_pk_mul_f32 v[136:137], v[100:101], v[144:145] op_sel_hi:[1,0]
	v_add_f32_e32 v140, 1.0, v140
	v_mul_f32_e32 v136, 0xbfb8aa3b, v136
	v_exp_f32_e32 v136, v136
	v_rcp_f32_e32 v146, v140
	v_mul_f32_e32 v140, 0xbfb8aa3b, v141
	v_exp_f32_e32 v140, v140
	v_add_f32_e32 v136, 1.0, v136
	v_rcp_f32_e32 v148, v136
	v_mul_f32_e32 v136, 0xbfb8aa3b, v137
	v_exp_f32_e32 v136, v136
	v_add_f32_e32 v140, 1.0, v140
	v_rcp_f32_e32 v147, v140
	v_mov_b32_e32 v141, v1
	v_add_f32_e32 v136, 1.0, v136
	v_rcp_f32_e32 v149, v136
	v_mov_b64_e32 v[136:137], s[52:53]
	v_mad_i64_i32 v[136:137], s[68:69], v139, s67, v[136:137]
	v_lshlrev_b32_e32 v139, 7, v182
	v_and_b32_e32 v140, 0x3e780, v139
	v_lshl_add_u64 v[136:137], v[136:137], 0, v[140:141]
	v_lshl_add_u64 v[136:137], v[136:137], 0, v[0:1]
	flat_store_dwordx4 v[136:137], v[146:149]
	v_pk_mul_f32 v[140:141], v[92:93], v[144:145] op_sel_hi:[1,0]
	s_nop 0
	v_pk_mul_f32 v[146:147], v[90:91], v[144:145] op_sel_hi:[1,0]
	s_nop 0
	v_mul_f32_e32 v0, 0xbfb8aa3b, v146
	v_exp_f32_e32 v0, v0
	s_nop 0
	v_add_f32_e32 v0, 1.0, v0
	v_rcp_f32_e32 v146, v0
	v_mul_f32_e32 v0, 0xbfb8aa3b, v147
	v_exp_f32_e32 v0, v0
	s_nop 0
	v_add_f32_e32 v0, 1.0, v0
	v_rcp_f32_e32 v147, v0
	v_mul_f32_e32 v0, 0xbfb8aa3b, v140
	v_exp_f32_e32 v0, v0
	s_nop 0
	v_add_f32_e32 v0, 1.0, v0
	v_rcp_f32_e32 v148, v0
	v_mul_f32_e32 v0, 0xbfb8aa3b, v141
	v_exp_f32_e32 v0, v0
	v_pk_mul_f32 v[140:141], v[88:89], v[142:143] op_sel_hi:[1,0]
	v_add_f32_e32 v0, 1.0, v0
	v_rcp_f32_e32 v149, v0
	flat_store_dwordx4 v[136:137], v[146:149] offset:64
	s_nop 1
	v_pk_mul_f32 v[146:147], v[86:87], v[142:143] op_sel_hi:[1,0]
	s_nop 0
	v_mul_f32_e32 v0, 0xbfb8aa3b, v146
	v_exp_f32_e32 v0, v0
	s_nop 0
	v_add_f32_e32 v0, 1.0, v0
	v_rcp_f32_e32 v146, v0
	v_mul_f32_e32 v0, 0xbfb8aa3b, v147
	v_exp_f32_e32 v0, v0
	s_nop 0
	v_add_f32_e32 v0, 1.0, v0
	v_rcp_f32_e32 v147, v0
	v_mul_f32_e32 v0, 0xbfb8aa3b, v140
	v_exp_f32_e32 v0, v0
	s_nop 0
	v_add_f32_e32 v0, 1.0, v0
	v_rcp_f32_e32 v148, v0
	v_mul_f32_e32 v0, 0xbfb8aa3b, v141
	v_exp_f32_e32 v0, v0
	v_pk_mul_f32 v[140:141], v[84:85], v[142:143] op_sel_hi:[1,0]
	v_add_f32_e32 v0, 1.0, v0
	v_rcp_f32_e32 v149, v0
	flat_store_dwordx4 v[136:137], v[146:149] offset:2048
	s_nop 1
	v_pk_mul_f32 v[146:147], v[82:83], v[142:143] op_sel_hi:[1,0]
	s_nop 0
	v_mul_f32_e32 v0, 0xbfb8aa3b, v146
	v_exp_f32_e32 v0, v0
	s_nop 0
	v_add_f32_e32 v0, 1.0, v0
	v_rcp_f32_e32 v146, v0
	v_mul_f32_e32 v0, 0xbfb8aa3b, v147
	v_exp_f32_e32 v0, v0
	s_nop 0
	v_add_f32_e32 v0, 1.0, v0
	v_rcp_f32_e32 v147, v0
	v_mul_f32_e32 v0, 0xbfb8aa3b, v140
	v_exp_f32_e32 v0, v0
	s_nop 0
	v_add_f32_e32 v0, 1.0, v0
	v_rcp_f32_e32 v148, v0
	v_mul_f32_e32 v0, 0xbfb8aa3b, v141
	v_exp_f32_e32 v0, v0
	v_pk_mul_f32 v[140:141], v[80:81], v[138:139] op_sel_hi:[1,0]
	v_add_f32_e32 v0, 1.0, v0
	v_rcp_f32_e32 v149, v0
	flat_store_dwordx4 v[136:137], v[146:149] offset:2112
	s_nop 1
	v_pk_mul_f32 v[146:147], v[78:79], v[138:139] op_sel_hi:[1,0]
	v_add_co_u32_e32 v136, vcc, s70, v136
	v_mul_f32_e32 v0, 0xbfb8aa3b, v146
	v_exp_f32_e32 v0, v0
	v_addc_co_u32_e32 v137, vcc, 0, v137, vcc
	v_add_f32_e32 v0, 1.0, v0
	v_rcp_f32_e32 v146, v0
	v_mul_f32_e32 v0, 0xbfb8aa3b, v147
	v_exp_f32_e32 v0, v0
	s_nop 0
	v_add_f32_e32 v0, 1.0, v0
	v_rcp_f32_e32 v147, v0
	v_mul_f32_e32 v0, 0xbfb8aa3b, v140
	v_exp_f32_e32 v0, v0
	s_nop 0
	v_add_f32_e32 v0, 1.0, v0
	v_rcp_f32_e32 v148, v0
	v_mul_f32_e32 v0, 0xbfb8aa3b, v141
	v_exp_f32_e32 v0, v0
	v_pk_mul_f32 v[140:141], v[76:77], v[138:139] op_sel_hi:[1,0]
	v_add_f32_e32 v0, 1.0, v0
	v_rcp_f32_e32 v149, v0
	flat_store_dwordx4 v[136:137], v[146:149]
	s_nop 1
	v_pk_mul_f32 v[146:147], v[74:75], v[138:139] op_sel_hi:[1,0]
	s_nop 0
	v_mul_f32_e32 v0, 0xbfb8aa3b, v146
	v_exp_f32_e32 v0, v0
	s_nop 0
	v_add_f32_e32 v0, 1.0, v0
	v_rcp_f32_e32 v146, v0
	v_mul_f32_e32 v0, 0xbfb8aa3b, v147
	v_exp_f32_e32 v0, v0
	s_nop 0
	v_add_f32_e32 v0, 1.0, v0
	v_rcp_f32_e32 v147, v0
	v_mul_f32_e32 v0, 0xbfb8aa3b, v140
	v_exp_f32_e32 v0, v0
	s_nop 0
	v_add_f32_e32 v0, 1.0, v0
	v_rcp_f32_e32 v148, v0
	v_mul_f32_e32 v0, 0xbfb8aa3b, v141
	v_exp_f32_e32 v0, v0
	v_pk_mul_f32 v[140:141], v[72:73], v[134:135] op_sel_hi:[1,0]
	v_add_f32_e32 v0, 1.0, v0
	v_rcp_f32_e32 v149, v0
	flat_store_dwordx4 v[136:137], v[146:149] offset:64
	s_nop 1
	v_pk_mul_f32 v[146:147], v[70:71], v[134:135] op_sel_hi:[1,0]
	s_nop 0
	v_mul_f32_e32 v0, 0xbfb8aa3b, v146
	v_exp_f32_e32 v0, v0
	s_nop 0
	v_add_f32_e32 v0, 1.0, v0
	v_rcp_f32_e32 v146, v0
	v_mul_f32_e32 v0, 0xbfb8aa3b, v147
	v_exp_f32_e32 v0, v0
	s_nop 0
	v_add_f32_e32 v0, 1.0, v0
	v_rcp_f32_e32 v147, v0
	v_mul_f32_e32 v0, 0xbfb8aa3b, v140
	v_exp_f32_e32 v0, v0
	s_nop 0
	v_add_f32_e32 v0, 1.0, v0
	v_rcp_f32_e32 v148, v0
	v_mul_f32_e32 v0, 0xbfb8aa3b, v141
	v_exp_f32_e32 v0, v0
	v_pk_mul_f32 v[140:141], v[68:69], v[134:135] op_sel_hi:[1,0]
	v_add_f32_e32 v0, 1.0, v0
	v_rcp_f32_e32 v149, v0
	flat_store_dwordx4 v[136:137], v[146:149] offset:2048
	s_nop 1
	v_pk_mul_f32 v[146:147], v[66:67], v[134:135] op_sel_hi:[1,0]
	s_nop 0
	v_mul_f32_e32 v0, 0xbfb8aa3b, v146
	v_exp_f32_e32 v0, v0
	s_nop 0
	v_add_f32_e32 v0, 1.0, v0
	v_rcp_f32_e32 v146, v0
	v_mul_f32_e32 v0, 0xbfb8aa3b, v147
	v_exp_f32_e32 v0, v0
	s_nop 0
	v_add_f32_e32 v0, 1.0, v0
	v_rcp_f32_e32 v147, v0
	v_mul_f32_e32 v0, 0xbfb8aa3b, v140
	v_exp_f32_e32 v0, v0
	s_nop 0
	v_add_f32_e32 v0, 1.0, v0
	v_rcp_f32_e32 v148, v0
	v_mul_f32_e32 v0, 0xbfb8aa3b, v141
	v_exp_f32_e32 v0, v0
	s_nop 0
	v_add_f32_e32 v0, 1.0, v0
	v_rcp_f32_e32 v149, v0
	flat_store_dwordx4 v[136:137], v[146:149] offset:2112
